# attention: cross-half permlane max moved into the rare rescale path (branch decision unchanged); barrier spin cap raised
# speedup vs baseline: 1.0042x; 1.0042x over previous
; DI float xmax32(float x) { auto t = __builtin_amdgcn_permlane32_swap(__float_as_uint(x), __float_as_uint(x), false, false); return fmaxf(__uint_as_float(t[0]), __uint_as_float(t[1])); }
; template <int DK, int DV>
; DI void attn_map(f32x16 (&O)[DV / 32], float& lsum, const u16* qrow, const u16* K1, int ldk1, const u16* K2, int ldk2, const u16* Vt, int nkeys, char* smem) {
;     ...
;     float mx0 = fmaxf(fmaxf(s[0][0], s[0][1]), s[0][2]), mx1 = fmaxf(fmaxf(s[1][0], s[1][1]), s[1][2]);
; #pragma unroll
;     for (int i = 3; i < 15; i += 2) { mx0 = fmaxf(fmaxf(mx0, s[0][i]), s[0][i + 1]); mx1 = fmaxf(fmaxf(mx1, s[1][i]), s[1][i + 1]); }
;     float mx = fmaxf(fmaxf(mx0, mx1), fmaxf(s[0][15], s[1][15]));
;     mx = xmax32(mx);
;     const bool first = (k0 == 0);
;     if (first || __any(mx > 6.f)) {
;       float dl = first ? mx : fmaxf(mx, 0.f);
;       float alpha = __builtin_amdgcn_exp2f(-dl);
; #pragma unroll
;       for (int i = 0; i < 16; ++i) { negm[i] -= dl; lacc[i] *= alpha; }
; #pragma unroll
;       for (int dd = 0; dd < DV / 32; ++dd)
; #pragma unroll
;         for (int i = 0; i < 16; ++i) O[dd][i] *= alpha;
; #pragma unroll
;       for (int j = 0; j < 2; ++j)
; #pragma unroll
;         for (int i = 0; i < 16; ++i) s[j][i] -= dl;
;     }
.Lqk_join_A:
	s_nop 0
	v_max3_f32 v194, v96, v97, v98
	v_lshl_add_u64 v[176:177], v[176:177], 0, s[56:57]
	v_lshl_add_u64 v[178:179], v[178:179], 0, s[56:57]
	v_lshl_add_u64 v[180:181], v[180:181], 0, s[56:57]
	v_lshl_add_u64 v[182:183], v[182:183], 0, s[56:57]
	v_lshl_add_u64 v[184:185], v[184:185], 0, s[58:59]
	v_lshl_add_u64 v[186:187], v[186:187], 0, s[58:59]
	v_mov_b64_e32 v[232:233], s[48:49]
	v_mov_b64_e32 v[234:235], s[50:51]
	s_nop 0
	v_max3_f32 v195, v112, v113, v114
	v_max3_f32 v194, v194, v99, v100
	v_max3_f32 v195, v195, v115, v116
	v_max3_f32 v194, v194, v101, v102
	v_max3_f32 v195, v195, v117, v118
	v_max3_f32 v194, v194, v103, v104
	v_max3_f32 v195, v195, v119, v120
	v_max3_f32 v194, v194, v105, v106
	v_max3_f32 v195, v195, v121, v122
	v_max3_f32 v194, v194, v107, v108
	v_max3_f32 v195, v195, v123, v124
	v_max_f32_e32 v196, v127, v127
	v_max_f32_e32 v197, v111, v111
	v_max3_f32 v194, v194, v109, v110
	v_max3_f32 v195, v195, v125, v126
	v_max_f32_e32 v196, v197, v196
	v_max3_f32 v194, v194, v195, v196
	v_cmp_lt_f32_e32 vcc, s45, v194
	s_cbranch_vccz .LBB0_381
	v_mov_b32_e32 v195, v194
	s_nop 1
	v_permlane32_swap_b32_e32 v194, v195
	v_max_f32_e32 v195, v195, v195
	v_max_f32_e32 v194, v194, v194
	v_max_f32_e32 v194, v194, v195
	v_max_f32_e32 v194, v194, v194
	v_max_f32_e32 v195, 0, v194
	v_exp_f32_e64 v194, -v195
	v_sub_f32_e32 v31, v31, v195
	v_sub_f32_e32 v30, v30, v195
	v_sub_f32_e32 v29, v29, v195
	v_pk_mul_f32 v[62:63], v[62:63], v[194:195] op_sel_hi:[1,0]
	v_pk_mul_f32 v[60:61], v[60:61], v[194:195] op_sel_hi:[1,0]
	v_pk_mul_f32 v[58:59], v[58:59], v[194:195] op_sel_hi:[1,0]
	v_pk_mul_f32 v[56:57], v[56:57], v[194:195] op_sel_hi:[1,0]
	v_pk_mul_f32 v[54:55], v[54:55], v[194:195] op_sel_hi:[1,0]
	v_pk_mul_f32 v[52:53], v[52:53], v[194:195] op_sel_hi:[1,0]
	v_pk_mul_f32 v[50:51], v[50:51], v[194:195] op_sel_hi:[1,0]
	v_pk_mul_f32 v[48:49], v[48:49], v[194:195] op_sel_hi:[1,0]
	v_pk_mul_f32 v[46:47], v[46:47], v[194:195] op_sel_hi:[1,0]
	v_pk_mul_f32 v[44:45], v[44:45], v[194:195] op_sel_hi:[1,0]
	v_pk_mul_f32 v[42:43], v[42:43], v[194:195] op_sel_hi:[1,0]
	v_pk_mul_f32 v[40:41], v[40:41], v[194:195] op_sel_hi:[1,0]
	v_pk_mul_f32 v[38:39], v[38:39], v[194:195] op_sel_hi:[1,0]
	v_pk_mul_f32 v[36:37], v[36:37], v[194:195] op_sel_hi:[1,0]
	v_pk_mul_f32 v[34:35], v[34:35], v[194:195] op_sel_hi:[1,0]
	v_pk_mul_f32 v[32:33], v[32:33], v[194:195] op_sel_hi:[1,0]
	v_pk_mul_f32 v[78:79], v[78:79], v[194:195] op_sel_hi:[1,0]
	v_pk_mul_f32 v[76:77], v[76:77], v[194:195] op_sel_hi:[1,0]
	v_pk_mul_f32 v[74:75], v[74:75], v[194:195] op_sel_hi:[1,0]
	v_pk_mul_f32 v[72:73], v[72:73], v[194:195] op_sel_hi:[1,0]
	v_pk_mul_f32 v[70:71], v[70:71], v[194:195] op_sel_hi:[1,0]
	v_pk_mul_f32 v[68:69], v[68:69], v[194:195] op_sel_hi:[1,0]
	v_pk_mul_f32 v[66:67], v[66:67], v[194:195] op_sel_hi:[1,0]
	v_pk_mul_f32 v[64:65], v[64:65], v[194:195] op_sel_hi:[1,0]
	v_pk_mul_f32 v[94:95], v[94:95], v[194:195] op_sel_hi:[1,0]
	v_pk_mul_f32 v[92:93], v[92:93], v[194:195] op_sel_hi:[1,0]
	v_pk_mul_f32 v[90:91], v[90:91], v[194:195] op_sel_hi:[1,0]
	v_pk_mul_f32 v[88:89], v[88:89], v[194:195] op_sel_hi:[1,0]
	v_pk_mul_f32 v[86:87], v[86:87], v[194:195] op_sel_hi:[1,0]
	v_pk_mul_f32 v[84:85], v[84:85], v[194:195] op_sel_hi:[1,0]
	v_pk_mul_f32 v[82:83], v[82:83], v[194:195] op_sel_hi:[1,0]
	v_pk_mul_f32 v[80:81], v[80:81], v[194:195] op_sel_hi:[1,0]
	v_sub_f32_e32 v28, v28, v195
	v_sub_f32_e32 v27, v27, v195
	v_sub_f32_e32 v26, v26, v195
	v_sub_f32_e32 v25, v25, v195
	v_sub_f32_e32 v24, v24, v195
	v_sub_f32_e32 v23, v23, v195
	v_sub_f32_e32 v22, v22, v195
	v_sub_f32_e32 v21, v21, v195
	v_sub_f32_e32 v20, v20, v195
	v_sub_f32_e32 v19, v19, v195
	v_sub_f32_e32 v18, v18, v195
	v_sub_f32_e32 v17, v17, v195
	v_sub_f32_e32 v16, v16, v195
	v_sub_f32_e32 v96, v96, v195
	v_sub_f32_e32 v97, v97, v195
	v_sub_f32_e32 v98, v98, v195
	v_sub_f32_e32 v99, v99, v195
	v_sub_f32_e32 v100, v100, v195
	v_sub_f32_e32 v101, v101, v195
	v_sub_f32_e32 v102, v102, v195
	v_sub_f32_e32 v103, v103, v195
	v_sub_f32_e32 v104, v104, v195
	v_sub_f32_e32 v105, v105, v195
	v_sub_f32_e32 v106, v106, v195
	v_sub_f32_e32 v107, v107, v195
	v_sub_f32_e32 v108, v108, v195
	v_sub_f32_e32 v109, v109, v195
	v_sub_f32_e32 v110, v110, v195
	v_sub_f32_e32 v111, v111, v195
	v_sub_f32_e32 v112, v112, v195
	v_sub_f32_e32 v113, v113, v195
	v_sub_f32_e32 v114, v114, v195
	v_sub_f32_e32 v115, v115, v195
	v_sub_f32_e32 v116, v116, v195
	v_sub_f32_e32 v117, v117, v195
	v_sub_f32_e32 v118, v118, v195
	v_sub_f32_e32 v119, v119, v195
	v_sub_f32_e32 v120, v120, v195
	v_sub_f32_e32 v121, v121, v195
	v_sub_f32_e32 v122, v122, v195
	v_sub_f32_e32 v123, v123, v195
	v_sub_f32_e32 v124, v124, v195
	v_sub_f32_e32 v125, v125, v195
	v_sub_f32_e32 v126, v126, v195
	v_sub_f32_e32 v127, v127, v195
	v_pk_mul_f32 v[14:15], v[14:15], v[194:195] op_sel_hi:[1,0]
	v_pk_mul_f32 v[12:13], v[12:13], v[194:195] op_sel_hi:[1,0]
	v_pk_mul_f32 v[10:11], v[10:11], v[194:195] op_sel_hi:[1,0]
	v_pk_mul_f32 v[8:9], v[8:9], v[194:195] op_sel_hi:[1,0]
	v_pk_mul_f32 v[6:7], v[6:7], v[194:195] op_sel_hi:[1,0]
	v_pk_mul_f32 v[4:5], v[4:5], v[194:195] op_sel_hi:[1,0]
	v_pk_mul_f32 v[2:3], v[2:3], v[194:195] op_sel_hi:[1,0]
	v_pk_mul_f32 v[0:1], v[0:1], v[194:195] op_sel_hi:[1,0]
	s_branch .LBB0_381

; DI float xmax32(float x) { auto t = __builtin_amdgcn_permlane32_swap(__float_as_uint(x), __float_as_uint(x), false, false); return fmaxf(__uint_as_float(t[0]), __uint_as_float(t[1])); }
; template <int DK, int DV>
; DI void attn_map(f32x16 (&O)[DV / 32], float& lsum, const u16* qrow, const u16* K1, int ldk1, const u16* K2, int ldk2, const u16* Vt, int nkeys, char* smem) {
;     ...
;     float mx0 = fmaxf(fmaxf(s[0][0], s[0][1]), s[0][2]), mx1 = fmaxf(fmaxf(s[1][0], s[1][1]), s[1][2]);
; #pragma unroll
;     for (int i = 3; i < 15; i += 2) { mx0 = fmaxf(fmaxf(mx0, s[0][i]), s[0][i + 1]); mx1 = fmaxf(fmaxf(mx1, s[1][i]), s[1][i + 1]); }
;     float mx = fmaxf(fmaxf(mx0, mx1), fmaxf(s[0][15], s[1][15]));
;     mx = xmax32(mx);
;     const bool first = (k0 == 0);
;     if (first || __any(mx > 6.f)) {
;       float dl = first ? mx : fmaxf(mx, 0.f);
;       float alpha = __builtin_amdgcn_exp2f(-dl);
; #pragma unroll
;       for (int i = 0; i < 16; ++i) { negm[i] -= dl; lacc[i] *= alpha; }
; #pragma unroll
;       for (int dd = 0; dd < DV / 32; ++dd)
; #pragma unroll
;         for (int i = 0; i < 16; ++i) O[dd][i] *= alpha;
; #pragma unroll
;       for (int j = 0; j < 2; ++j)
; #pragma unroll
;         for (int i = 0; i < 16; ++i) s[j][i] -= dl;
;     }
.Lqk_join_B:
	s_nop 0
	v_max3_f32 v196, v96, v97, v98
	v_lshl_add_u64 v[176:177], v[176:177], 0, s[56:57]
	v_lshl_add_u64 v[178:179], v[178:179], 0, s[56:57]
	v_lshl_add_u64 v[180:181], v[180:181], 0, s[56:57]
	v_lshl_add_u64 v[182:183], v[182:183], 0, s[56:57]
	v_lshl_add_u64 v[184:185], v[184:185], 0, s[58:59]
	v_lshl_add_u64 v[186:187], v[186:187], 0, s[58:59]
	v_mov_b64_e32 v[232:233], s[48:49]
	v_mov_b64_e32 v[234:235], s[50:51]
	s_nop 0
	v_max3_f32 v197, v112, v113, v114
	v_max3_f32 v196, v196, v99, v100
	v_max3_f32 v197, v197, v115, v116
	v_max3_f32 v196, v196, v101, v102
	v_max3_f32 v197, v197, v117, v118
	v_max3_f32 v196, v196, v103, v104
	v_max3_f32 v197, v197, v119, v120
	v_max3_f32 v196, v196, v105, v106
	v_max3_f32 v197, v197, v121, v122
	v_max3_f32 v196, v196, v107, v108
	v_max3_f32 v197, v197, v123, v124
	v_max_f32_e32 v198, v127, v127
	v_max_f32_e32 v199, v111, v111
	v_max3_f32 v196, v196, v109, v110
	v_max3_f32 v197, v197, v125, v126
	v_max_f32_e32 v198, v199, v198
	v_max3_f32 v196, v196, v197, v198
	v_cmp_lt_f32_e32 vcc, s45, v196
	s_cbranch_vccz .LBB0_403
	v_mov_b32_e32 v197, v196
	s_nop 1
	v_permlane32_swap_b32_e32 v196, v197
	v_max_f32_e32 v197, v197, v197
	v_max_f32_e32 v196, v196, v196
	v_max_f32_e32 v196, v196, v197
	v_max_f32_e32 v196, v196, v196
	v_max_f32_e32 v197, 0, v196
	v_exp_f32_e64 v196, -v197
	v_sub_f32_e32 v95, v95, v197
	v_sub_f32_e32 v94, v94, v197
	v_sub_f32_e32 v93, v93, v197
	v_pk_mul_f32 v[62:63], v[62:63], v[196:197] op_sel_hi:[1,0]
	v_pk_mul_f32 v[60:61], v[60:61], v[196:197] op_sel_hi:[1,0]
	v_pk_mul_f32 v[58:59], v[58:59], v[196:197] op_sel_hi:[1,0]
	v_pk_mul_f32 v[56:57], v[56:57], v[196:197] op_sel_hi:[1,0]
	v_pk_mul_f32 v[54:55], v[54:55], v[196:197] op_sel_hi:[1,0]
	v_pk_mul_f32 v[52:53], v[52:53], v[196:197] op_sel_hi:[1,0]
	v_pk_mul_f32 v[50:51], v[50:51], v[196:197] op_sel_hi:[1,0]
	v_pk_mul_f32 v[48:49], v[48:49], v[196:197] op_sel_hi:[1,0]
	v_pk_mul_f32 v[46:47], v[46:47], v[196:197] op_sel_hi:[1,0]
	v_pk_mul_f32 v[44:45], v[44:45], v[196:197] op_sel_hi:[1,0]
	v_pk_mul_f32 v[42:43], v[42:43], v[196:197] op_sel_hi:[1,0]
	v_pk_mul_f32 v[40:41], v[40:41], v[196:197] op_sel_hi:[1,0]
	v_pk_mul_f32 v[38:39], v[38:39], v[196:197] op_sel_hi:[1,0]
	v_pk_mul_f32 v[36:37], v[36:37], v[196:197] op_sel_hi:[1,0]
	v_pk_mul_f32 v[34:35], v[34:35], v[196:197] op_sel_hi:[1,0]
	v_pk_mul_f32 v[32:33], v[32:33], v[196:197] op_sel_hi:[1,0]
	v_pk_mul_f32 v[30:31], v[30:31], v[196:197] op_sel_hi:[1,0]
	v_pk_mul_f32 v[28:29], v[28:29], v[196:197] op_sel_hi:[1,0]
	v_pk_mul_f32 v[26:27], v[26:27], v[196:197] op_sel_hi:[1,0]
	v_pk_mul_f32 v[24:25], v[24:25], v[196:197] op_sel_hi:[1,0]
	v_pk_mul_f32 v[22:23], v[22:23], v[196:197] op_sel_hi:[1,0]
	v_pk_mul_f32 v[20:21], v[20:21], v[196:197] op_sel_hi:[1,0]
	v_pk_mul_f32 v[18:19], v[18:19], v[196:197] op_sel_hi:[1,0]
	v_pk_mul_f32 v[16:17], v[16:17], v[196:197] op_sel_hi:[1,0]
	v_pk_mul_f32 v[14:15], v[14:15], v[196:197] op_sel_hi:[1,0]
	v_pk_mul_f32 v[12:13], v[12:13], v[196:197] op_sel_hi:[1,0]
	v_pk_mul_f32 v[10:11], v[10:11], v[196:197] op_sel_hi:[1,0]
	v_pk_mul_f32 v[8:9], v[8:9], v[196:197] op_sel_hi:[1,0]
	v_pk_mul_f32 v[6:7], v[6:7], v[196:197] op_sel_hi:[1,0]
	v_pk_mul_f32 v[4:5], v[4:5], v[196:197] op_sel_hi:[1,0]
	v_pk_mul_f32 v[2:3], v[2:3], v[196:197] op_sel_hi:[1,0]
	v_pk_mul_f32 v[0:1], v[0:1], v[196:197] op_sel_hi:[1,0]
	v_sub_f32_e32 v92, v92, v197
	v_sub_f32_e32 v91, v91, v197
	v_sub_f32_e32 v90, v90, v197
	v_sub_f32_e32 v89, v89, v197
	v_sub_f32_e32 v88, v88, v197
	v_sub_f32_e32 v87, v87, v197
	v_sub_f32_e32 v86, v86, v197
	v_sub_f32_e32 v85, v85, v197
	v_sub_f32_e32 v84, v84, v197
	v_sub_f32_e32 v83, v83, v197
	v_sub_f32_e32 v82, v82, v197
	v_sub_f32_e32 v81, v81, v197
	v_sub_f32_e32 v80, v80, v197
	v_sub_f32_e32 v96, v96, v197
	v_sub_f32_e32 v97, v97, v197
	v_sub_f32_e32 v98, v98, v197
	v_sub_f32_e32 v99, v99, v197
	v_sub_f32_e32 v100, v100, v197
	v_sub_f32_e32 v101, v101, v197
	v_sub_f32_e32 v102, v102, v197
	v_sub_f32_e32 v103, v103, v197
	v_sub_f32_e32 v104, v104, v197
	v_sub_f32_e32 v105, v105, v197
	v_sub_f32_e32 v106, v106, v197
	v_sub_f32_e32 v107, v107, v197
	v_sub_f32_e32 v108, v108, v197
	v_sub_f32_e32 v109, v109, v197
	v_sub_f32_e32 v110, v110, v197
	v_sub_f32_e32 v111, v111, v197
	v_sub_f32_e32 v112, v112, v197
	v_sub_f32_e32 v113, v113, v197
	v_sub_f32_e32 v114, v114, v197
	v_sub_f32_e32 v115, v115, v197
	v_sub_f32_e32 v116, v116, v197
	v_sub_f32_e32 v117, v117, v197
	v_sub_f32_e32 v118, v118, v197
	v_sub_f32_e32 v119, v119, v197
	v_sub_f32_e32 v120, v120, v197
	v_sub_f32_e32 v121, v121, v197
	v_sub_f32_e32 v122, v122, v197
	v_sub_f32_e32 v123, v123, v197
	v_sub_f32_e32 v124, v124, v197
	v_sub_f32_e32 v125, v125, v197
	v_sub_f32_e32 v126, v126, v197
	v_sub_f32_e32 v127, v127, v197
	v_pk_mul_f32 v[78:79], v[78:79], v[196:197] op_sel_hi:[1,0]
	v_pk_mul_f32 v[76:77], v[76:77], v[196:197] op_sel_hi:[1,0]
	v_pk_mul_f32 v[74:75], v[74:75], v[196:197] op_sel_hi:[1,0]
	v_pk_mul_f32 v[72:73], v[72:73], v[196:197] op_sel_hi:[1,0]
	v_pk_mul_f32 v[70:71], v[70:71], v[196:197] op_sel_hi:[1,0]
	v_pk_mul_f32 v[68:69], v[68:69], v[196:197] op_sel_hi:[1,0]
	v_pk_mul_f32 v[66:67], v[66:67], v[196:197] op_sel_hi:[1,0]
	v_pk_mul_f32 v[64:65], v[64:65], v[196:197] op_sel_hi:[1,0]
	s_branch .LBB0_403

; DI float xmax32(float x) { auto t = __builtin_amdgcn_permlane32_swap(__float_as_uint(x), __float_as_uint(x), false, false); return fmaxf(__uint_as_float(t[0]), __uint_as_float(t[1])); }
; template <int DK, int DV>
; DI void attn_map(f32x16 (&O)[DV / 32], float& lsum, const u16* qrow, const u16* K1, int ldk1, const u16* K2, int ldk2, const u16* Vt, int nkeys, char* smem) {
;     ...
;     float mx0 = fmaxf(fmaxf(s[0][0], s[0][1]), s[0][2]), mx1 = fmaxf(fmaxf(s[1][0], s[1][1]), s[1][2]);
; #pragma unroll
;     for (int i = 3; i < 15; i += 2) { mx0 = fmaxf(fmaxf(mx0, s[0][i]), s[0][i + 1]); mx1 = fmaxf(fmaxf(mx1, s[1][i]), s[1][i + 1]); }
;     float mx = fmaxf(fmaxf(mx0, mx1), fmaxf(s[0][15], s[1][15]));
;     mx = xmax32(mx);
;     const bool first = (k0 == 0);
;     if (first || __any(mx > 6.f)) {
;       float dl = first ? mx : fmaxf(mx, 0.f);
;       float alpha = __builtin_amdgcn_exp2f(-dl);
; #pragma unroll
;       for (int i = 0; i < 16; ++i) { negm[i] -= dl; lacc[i] *= alpha; }
; #pragma unroll
;       for (int dd = 0; dd < DV / 32; ++dd)
; #pragma unroll
;         for (int i = 0; i < 16; ++i) O[dd][i] *= alpha;
; #pragma unroll
;       for (int j = 0; j < 2; ++j)
; #pragma unroll
;         for (int i = 0; i < 16; ++i) s[j][i] -= dl;
;     }
.Lqk_join_C:
	v_max3_f32 v173, v64, v65, v66
	v_lshl_add_u64 v[154:155], v[154:155], 0, s[56:57]
	v_lshl_add_u64 v[156:157], v[156:157], 0, s[56:57]
	v_mov_b64_e32 v[184:185], s[48:49]
	v_mov_b64_e32 v[186:187], s[50:51]
	s_nop 5
	v_max3_f32 v174, v80, v81, v82
	v_max3_f32 v173, v173, v67, v68
	v_max3_f32 v174, v174, v83, v84
	v_max3_f32 v173, v173, v69, v70
	v_max3_f32 v174, v174, v85, v86
	v_max3_f32 v173, v173, v71, v72
	v_max3_f32 v174, v174, v87, v88
	v_max3_f32 v173, v173, v73, v74
	v_max3_f32 v174, v174, v89, v90
	v_max3_f32 v173, v173, v75, v76
	v_max3_f32 v174, v174, v91, v92
	v_max_f32_e32 v175, v95, v95
	v_max_f32_e32 v176, v79, v79
	v_max3_f32 v173, v173, v77, v78
	v_max3_f32 v174, v174, v93, v94
	v_max_f32_e32 v175, v176, v175
	v_max3_f32 v173, v173, v174, v175
	v_cmp_lt_f32_e32 vcc, s45, v173
	s_cbranch_vccz .LBB0_440
	v_mov_b32_e32 v174, v173
	s_nop 1
	v_permlane32_swap_b32_e32 v173, v174
	v_max_f32_e32 v174, v174, v174
	v_max_f32_e32 v173, v173, v173
	v_max_f32_e32 v173, v173, v174
	v_max_f32_e32 v173, v173, v173
	v_max_f32_e32 v173, 0, v173
	v_exp_f32_e64 v174, -v173
	v_sub_f32_e32 v31, v31, v173
	v_sub_f32_e32 v30, v30, v173
	v_sub_f32_e32 v29, v29, v173
	v_pk_mul_f32 v[62:63], v[62:63], v[174:175] op_sel_hi:[1,0]
	v_pk_mul_f32 v[60:61], v[60:61], v[174:175] op_sel_hi:[1,0]
	v_pk_mul_f32 v[58:59], v[58:59], v[174:175] op_sel_hi:[1,0]
	v_pk_mul_f32 v[56:57], v[56:57], v[174:175] op_sel_hi:[1,0]
	v_pk_mul_f32 v[54:55], v[54:55], v[174:175] op_sel_hi:[1,0]
	v_pk_mul_f32 v[52:53], v[52:53], v[174:175] op_sel_hi:[1,0]
	v_pk_mul_f32 v[50:51], v[50:51], v[174:175] op_sel_hi:[1,0]
	v_pk_mul_f32 v[48:49], v[48:49], v[174:175] op_sel_hi:[1,0]
	v_pk_mul_f32 v[46:47], v[46:47], v[174:175] op_sel_hi:[1,0]
	v_pk_mul_f32 v[44:45], v[44:45], v[174:175] op_sel_hi:[1,0]
	v_pk_mul_f32 v[42:43], v[42:43], v[174:175] op_sel_hi:[1,0]
	v_pk_mul_f32 v[40:41], v[40:41], v[174:175] op_sel_hi:[1,0]
	v_pk_mul_f32 v[38:39], v[38:39], v[174:175] op_sel_hi:[1,0]
	v_pk_mul_f32 v[36:37], v[36:37], v[174:175] op_sel_hi:[1,0]
	v_pk_mul_f32 v[34:35], v[34:35], v[174:175] op_sel_hi:[1,0]
	v_pk_mul_f32 v[32:33], v[32:33], v[174:175] op_sel_hi:[1,0]
	v_sub_f32_e32 v28, v28, v173
	v_sub_f32_e32 v27, v27, v173
	v_sub_f32_e32 v26, v26, v173
	v_sub_f32_e32 v25, v25, v173
	v_sub_f32_e32 v24, v24, v173
	v_sub_f32_e32 v23, v23, v173
	v_sub_f32_e32 v22, v22, v173
	v_sub_f32_e32 v21, v21, v173
	v_sub_f32_e32 v20, v20, v173
	v_sub_f32_e32 v19, v19, v173
	v_sub_f32_e32 v18, v18, v173
	v_sub_f32_e32 v17, v17, v173
	v_sub_f32_e32 v16, v16, v173
	v_sub_f32_e32 v64, v64, v173
	v_sub_f32_e32 v65, v65, v173
	v_sub_f32_e32 v66, v66, v173
	v_sub_f32_e32 v67, v67, v173
	v_sub_f32_e32 v68, v68, v173
	v_sub_f32_e32 v69, v69, v173
	v_sub_f32_e32 v70, v70, v173
	v_sub_f32_e32 v71, v71, v173
	v_sub_f32_e32 v72, v72, v173
	v_sub_f32_e32 v73, v73, v173
	v_sub_f32_e32 v74, v74, v173
	v_sub_f32_e32 v75, v75, v173
	v_sub_f32_e32 v76, v76, v173
	v_sub_f32_e32 v77, v77, v173
	v_sub_f32_e32 v78, v78, v173
	v_sub_f32_e32 v79, v79, v173
	v_sub_f32_e32 v80, v80, v173
	v_sub_f32_e32 v81, v81, v173
	v_sub_f32_e32 v82, v82, v173
	v_sub_f32_e32 v83, v83, v173
	v_sub_f32_e32 v84, v84, v173
	v_sub_f32_e32 v85, v85, v173
	v_sub_f32_e32 v86, v86, v173
	v_sub_f32_e32 v87, v87, v173
	v_sub_f32_e32 v88, v88, v173
	v_sub_f32_e32 v89, v89, v173
	v_sub_f32_e32 v90, v90, v173
	v_sub_f32_e32 v91, v91, v173
	v_sub_f32_e32 v92, v92, v173
	v_sub_f32_e32 v93, v93, v173
	v_sub_f32_e32 v94, v94, v173
	v_sub_f32_e32 v95, v95, v173
	v_pk_mul_f32 v[14:15], v[14:15], v[174:175] op_sel_hi:[1,0]
	v_pk_mul_f32 v[12:13], v[12:13], v[174:175] op_sel_hi:[1,0]
	v_pk_mul_f32 v[10:11], v[10:11], v[174:175] op_sel_hi:[1,0]
	v_pk_mul_f32 v[8:9], v[8:9], v[174:175] op_sel_hi:[1,0]
	v_pk_mul_f32 v[6:7], v[6:7], v[174:175] op_sel_hi:[1,0]
	v_pk_mul_f32 v[4:5], v[4:5], v[174:175] op_sel_hi:[1,0]
	v_pk_mul_f32 v[2:3], v[2:3], v[174:175] op_sel_hi:[1,0]
	v_pk_mul_f32 v[0:1], v[0:1], v[174:175] op_sel_hi:[1,0]

; DI float xmax32(float x) { auto t = __builtin_amdgcn_permlane32_swap(__float_as_uint(x), __float_as_uint(x), false, false); return fmaxf(__uint_as_float(t[0]), __uint_as_float(t[1])); }
; template <int DK, int DV>
; DI void attn_map(f32x16 (&O)[DV / 32], float& lsum, const u16* qrow, const u16* K1, int ldk1, const u16* K2, int ldk2, const u16* Vt, int nkeys, char* smem) {
;     ...
;     float mx0 = fmaxf(fmaxf(s[0][0], s[0][1]), s[0][2]), mx1 = fmaxf(fmaxf(s[1][0], s[1][1]), s[1][2]);
; #pragma unroll
;     for (int i = 3; i < 15; i += 2) { mx0 = fmaxf(fmaxf(mx0, s[0][i]), s[0][i + 1]); mx1 = fmaxf(fmaxf(mx1, s[1][i]), s[1][i + 1]); }
;     float mx = fmaxf(fmaxf(mx0, mx1), fmaxf(s[0][15], s[1][15]));
;     mx = xmax32(mx);
;     const bool first = (k0 == 0);
;     if (first || __any(mx > 6.f)) {
;       float dl = first ? mx : fmaxf(mx, 0.f);
;       float alpha = __builtin_amdgcn_exp2f(-dl);
; #pragma unroll
;       for (int i = 0; i < 16; ++i) { negm[i] -= dl; lacc[i] *= alpha; }
; #pragma unroll
;       for (int dd = 0; dd < DV / 32; ++dd)
; #pragma unroll
;         for (int i = 0; i < 16; ++i) O[dd][i] *= alpha;
; #pragma unroll
;       for (int j = 0; j < 2; ++j)
; #pragma unroll
;         for (int i = 0; i < 16; ++i) s[j][i] -= dl;
;     }
.Lqk_join_D:
	s_nop 0
	v_max3_f32 v144, v64, v65, v66
	s_mov_b64 s[10:11], 0x4000
	v_lshl_add_u64 v[130:131], v[130:131], 0, s[56:57]
	v_lshl_add_u64 v[132:133], v[132:133], 0, s[56:57]
	v_lshl_add_u64 v[134:135], v[134:135], 0, s[10:11]
	v_lshl_add_u64 v[136:137], v[136:137], 0, s[10:11]
	v_mov_b64_e32 v[232:233], s[48:49]
	v_mov_b64_e32 v[234:235], s[50:51]
	s_nop 1
	v_max3_f32 v145, v80, v81, v82
	v_max3_f32 v144, v144, v67, v68
	v_max3_f32 v145, v145, v83, v84
	v_max3_f32 v144, v144, v69, v70
	v_max3_f32 v145, v145, v85, v86
	v_max3_f32 v144, v144, v71, v72
	v_max3_f32 v145, v145, v87, v88
	v_max3_f32 v144, v144, v73, v74
	v_max3_f32 v145, v145, v89, v90
	v_max3_f32 v144, v144, v75, v76
	v_max3_f32 v145, v145, v91, v92
	v_max_f32_e32 v146, v95, v95
	v_max_f32_e32 v147, v79, v79
	v_max3_f32 v144, v144, v77, v78
	v_max3_f32 v145, v145, v93, v94
	v_max_f32_e32 v146, v147, v146
	v_max3_f32 v144, v144, v145, v146
	v_cmp_lt_f32_e32 vcc, s45, v144
	s_cbranch_vccz .LBB0_446
	v_mov_b32_e32 v145, v144
	s_nop 1
	v_permlane32_swap_b32_e32 v144, v145
	v_max_f32_e32 v145, v145, v145
	v_max_f32_e32 v144, v144, v144
	v_max_f32_e32 v144, v144, v145
	v_max_f32_e32 v144, v144, v144
	v_max_f32_e32 v145, 0, v144
	v_exp_f32_e64 v144, -v145
	v_sub_f32_e32 v31, v31, v145
	v_sub_f32_e32 v30, v30, v145
	v_sub_f32_e32 v29, v29, v145
	v_pk_mul_f32 v[62:63], v[62:63], v[144:145] op_sel_hi:[1,0]
	v_pk_mul_f32 v[60:61], v[60:61], v[144:145] op_sel_hi:[1,0]
	v_pk_mul_f32 v[58:59], v[58:59], v[144:145] op_sel_hi:[1,0]
	v_pk_mul_f32 v[56:57], v[56:57], v[144:145] op_sel_hi:[1,0]
	v_pk_mul_f32 v[54:55], v[54:55], v[144:145] op_sel_hi:[1,0]
	v_pk_mul_f32 v[52:53], v[52:53], v[144:145] op_sel_hi:[1,0]
	v_pk_mul_f32 v[50:51], v[50:51], v[144:145] op_sel_hi:[1,0]
	v_pk_mul_f32 v[48:49], v[48:49], v[144:145] op_sel_hi:[1,0]
	v_pk_mul_f32 v[46:47], v[46:47], v[144:145] op_sel_hi:[1,0]
	v_pk_mul_f32 v[44:45], v[44:45], v[144:145] op_sel_hi:[1,0]
	v_pk_mul_f32 v[42:43], v[42:43], v[144:145] op_sel_hi:[1,0]
	v_pk_mul_f32 v[40:41], v[40:41], v[144:145] op_sel_hi:[1,0]
	v_pk_mul_f32 v[38:39], v[38:39], v[144:145] op_sel_hi:[1,0]
	v_pk_mul_f32 v[36:37], v[36:37], v[144:145] op_sel_hi:[1,0]
	v_pk_mul_f32 v[34:35], v[34:35], v[144:145] op_sel_hi:[1,0]
	v_pk_mul_f32 v[32:33], v[32:33], v[144:145] op_sel_hi:[1,0]
	v_sub_f32_e32 v28, v28, v145
	v_sub_f32_e32 v27, v27, v145
	v_sub_f32_e32 v26, v26, v145
	v_sub_f32_e32 v25, v25, v145
	v_sub_f32_e32 v24, v24, v145
	v_sub_f32_e32 v23, v23, v145
	v_sub_f32_e32 v22, v22, v145
	v_sub_f32_e32 v21, v21, v145
	v_sub_f32_e32 v20, v20, v145
	v_sub_f32_e32 v19, v19, v145
	v_sub_f32_e32 v18, v18, v145
	v_sub_f32_e32 v17, v17, v145
	v_sub_f32_e32 v16, v16, v145
	v_sub_f32_e32 v64, v64, v145
	v_sub_f32_e32 v65, v65, v145
	v_sub_f32_e32 v66, v66, v145
	v_sub_f32_e32 v67, v67, v145
	v_sub_f32_e32 v68, v68, v145
	v_sub_f32_e32 v69, v69, v145
	v_sub_f32_e32 v70, v70, v145
	v_sub_f32_e32 v71, v71, v145
	v_sub_f32_e32 v72, v72, v145
	v_sub_f32_e32 v73, v73, v145
	v_sub_f32_e32 v74, v74, v145
	v_sub_f32_e32 v75, v75, v145
	v_sub_f32_e32 v76, v76, v145
	v_sub_f32_e32 v77, v77, v145
	v_sub_f32_e32 v78, v78, v145
	v_sub_f32_e32 v79, v79, v145
	v_sub_f32_e32 v80, v80, v145
	v_sub_f32_e32 v81, v81, v145
	v_sub_f32_e32 v82, v82, v145
	v_sub_f32_e32 v83, v83, v145
	v_sub_f32_e32 v84, v84, v145
	v_sub_f32_e32 v85, v85, v145
	v_sub_f32_e32 v86, v86, v145
	v_sub_f32_e32 v87, v87, v145
	v_sub_f32_e32 v88, v88, v145
	v_sub_f32_e32 v89, v89, v145
	v_sub_f32_e32 v90, v90, v145
	v_sub_f32_e32 v91, v91, v145
	v_sub_f32_e32 v92, v92, v145
	v_sub_f32_e32 v93, v93, v145
	v_sub_f32_e32 v94, v94, v145
	v_sub_f32_e32 v95, v95, v145
	v_pk_mul_f32 v[14:15], v[14:15], v[144:145] op_sel_hi:[1,0]
	v_pk_mul_f32 v[12:13], v[12:13], v[144:145] op_sel_hi:[1,0]
	v_pk_mul_f32 v[10:11], v[10:11], v[144:145] op_sel_hi:[1,0]
	v_pk_mul_f32 v[8:9], v[8:9], v[144:145] op_sel_hi:[1,0]
	v_pk_mul_f32 v[6:7], v[6:7], v[144:145] op_sel_hi:[1,0]
	v_pk_mul_f32 v[4:5], v[4:5], v[144:145] op_sel_hi:[1,0]
	v_pk_mul_f32 v[2:3], v[2:3], v[144:145] op_sel_hi:[1,0]
	v_pk_mul_f32 v[0:1], v[0:1], v[144:145] op_sel_hi:[1,0]
	s_branch .LBB0_446

; __global__ void __launch_bounds__(256, 2) fwd_megakernel(Params P) {
;     ...
;         if (!store) grid.sync();
;       }
;     }
;     if (ph + 1 < P.ph_end) grid.sync();
.Lgs_loop:
	global_load_dword v1, v169, s[10:11] sc1
	s_waitcnt vmcnt(0)
	s_nop 0
	v_readfirstlane_b32 s12, v1
	s_and_b32 s12, s12, 0xffff0000
	s_cmp_lg_u32 s12, s14
	s_cbranch_scc1 .Lgs_exit
	s_sleep 1
	s_add_u32 s13, s13, 1
	s_cmp_lt_u32 s13, 0x1000000
	s_cbranch_scc1 .Lgs_loop
